# GLA-G3 output stage: three output tiles computed together with double-buffered operand reads instead of three serial MFMA chains
# speedup vs baseline: 1.0181x; 1.0027x over previous
; #define LAS __attribute__((address_space(3)))
; __device__ __forceinline__ bf16_t f2bf(float f) { unsigned u = __float_as_uint(f); u += 0x7FFFu + ((u >> 16) & 1u); return (bf16_t)(u >> 16); }
; __device__ __forceinline__ f32x4 mfma16(bf16x8 a, bf16x8 b, f32x4 c) { return __builtin_amdgcn_mfma_f32_16x16x32_bf16(a, b, c, 0, 0, 0); }
; __device__ __forceinline__ void gla_g3_item(int wv, const Params& p, int l, int b, int n, int h, LAS unsigned char* lds) {
;     ...
;     { const int dir = wave >> 2, mi = wave & 3;
;       bf16x8 a[2];
; #pragma unroll
;       for (int kk = 0; kk < 2; ++kk) a[kk] = *(const LAS bf16x8*)(lds + GL_Q + (dir * 64 + mi * 16 + fr) * 144 + kk * 64 + fq * 16);
; #pragma unroll
;       for (int ni = 0; ni < 4; ++ni) { f32x4 acc = (f32x4){0.f, 0.f, 0.f, 0.f};
; #pragma unroll
;           for (int kk = 0; kk < 2; ++kk) { const bf16x8 bb = *(const LAS bf16x8*)(lds + GL_K + (dir * 64 + ni * 16 + fr) * 144 + kk * 64 + fq * 16); acc = mfma16(a[kk], bb, acc); }
; #pragma unroll
;           for (int i = 0; i < 4; ++i) { const int t = mi * 16 + fq * 4 + i, sidx = ni * 16 + fr; const bool keep = dir ? (sidx >= t) : (sidx <= t);
;               *(LAS bf16_t*)(lds + GL_X + (dir * 64 + t) * 144 + sidx * 2) = f2bf(keep ? acc[i] : 0.f); } } }
.LBB0_954:
	s_or_b64 exec, exec, s[4:5]
	v_ashrrev_i32_e32 v3, 2, v2
	v_and_b32_e32 v3, 0xffffffc0, v3
	v_lshlrev_b32_e32 v4, 4, v82
	v_and_b32_e32 v26, 48, v4
	v_or_b32_e32 v4, v3, v81
	v_or_b32_e32 v5, v4, v26
	v_mul_lo_u32 v5, v5, s55
	v_add3_u32 v18, 0, v5, v0
	s_waitcnt lgkmcnt(0)
	s_barrier
	ds_read_b128 v[10:13], v18 offset:39424
	v_mad_u64_u32 v[4:5], s[4:5], v4, s55, v[38:39]
	ds_read_b128 v[14:17], v4 offset:57856
	ds_read_b128 v[18:21], v18 offset:39488
	ds_read_b128 v[22:25], v4 offset:57920
	s_waitcnt lgkmcnt(2)
	v_mfma_f32_16x16x32_bf16 v[14:17], v[10:13], v[14:17], 0
	v_or_b32_e32 v5, v26, v40
	v_cmp_le_u32_e32 vcc, v81, v5
	s_add_i32 s3, 0, 0x16000
	s_waitcnt lgkmcnt(0)
	v_mfma_f32_16x16x32_bf16 v[14:17], v[18:21], v[22:25], v[14:17]
	v_cndmask_b32_e64 v23, 0, 1, vcc
	v_cmp_ge_u32_e32 vcc, v81, v5
	v_lshl_add_u32 v22, v81, 1, s3
	v_or_b32_e32 v27, 1, v5
	v_cndmask_b32_e64 v24, 0, 1, vcc
	v_cmp_gt_u32_e32 vcc, s43, v2
	v_or_b32_e32 v29, 2, v5
	v_or_b32_e32 v32, 3, v5
	v_cndmask_b32_e32 v23, v24, v23, vcc
	v_and_b32_e32 v23, 1, v23
	v_cmp_eq_u32_e64 s[14:15], 1, v23
	v_and_b32_e32 v2, 64, v2
	v_add_u32_e32 v33, s87, v0
	v_cndmask_b32_e64 v14, 0, v14, s[14:15]
	v_bfe_u32 v23, v14, 16, 1
	v_add3_u32 v14, v14, v23, s54
	v_or_b32_e32 v23, v5, v3
	v_mul_lo_u32 v26, v23, s55
	v_add_u32_e32 v23, v22, v26
	v_cmp_gt_u32_e64 s[14:15], v81, v5
	ds_write_b16_d16_hi v23, v14
	v_mov_b32_e32 v61, v1
	v_cndmask_b32_e64 v14, 0, 1, s[14:15]
	v_cmp_le_u32_e64 s[14:15], v81, v27
	s_mov_b64 s[4:5], 0x800500
	s_nop 0
	v_cndmask_b32_e64 v23, 0, 1, s[14:15]
	v_cndmask_b32_e32 v14, v14, v23, vcc
	v_and_b32_e32 v14, 1, v14
	v_cmp_eq_u32_e64 s[14:15], 1, v14
	s_nop 1
	v_cndmask_b32_e64 v14, 0, v15, s[14:15]
	v_bfe_u32 v15, v14, 16, 1
	v_add3_u32 v14, v14, v15, s54
	v_or_b32_e32 v15, v27, v3
	v_mul_lo_u32 v28, v15, s55
	v_add_u32_e32 v15, v22, v28
	v_cmp_le_u32_e64 s[14:15], v81, v29
	ds_write_b16_d16_hi v15, v14
	s_nop 0
	v_cndmask_b32_e64 v14, 0, 1, s[14:15]
	v_cmp_ge_u32_e64 s[14:15], v81, v29
	s_nop 1
	v_cndmask_b32_e64 v15, 0, 1, s[14:15]
	v_cndmask_b32_e32 v14, v15, v14, vcc
	v_and_b32_e32 v14, 1, v14
	v_cmp_eq_u32_e64 s[14:15], 1, v14
	s_nop 1
	v_cndmask_b32_e64 v14, 0, v16, s[14:15]
	v_bfe_u32 v15, v14, 16, 1
	v_add3_u32 v14, v14, v15, s54
	v_or_b32_e32 v15, v29, v3
	v_mul_lo_u32 v31, v15, s55
	v_add_u32_e32 v15, v22, v31
	v_cmp_le_u32_e64 s[14:15], v81, v32
	ds_write_b16_d16_hi v15, v14
	v_or_b32_e32 v3, v32, v3
	v_cndmask_b32_e64 v14, 0, 1, s[14:15]
	v_cmp_ge_u32_e64 s[14:15], v81, v32
	v_mul_lo_u32 v3, v3, s55
	s_nop 0
	v_cndmask_b32_e64 v15, 0, 1, s[14:15]
	v_cndmask_b32_e32 v14, v15, v14, vcc
	v_and_b32_e32 v14, 1, v14
	v_cmp_eq_u32_e64 s[14:15], 1, v14
	s_nop 1
	v_cndmask_b32_e64 v14, 0, v17, s[14:15]
	v_bfe_u32 v15, v14, 16, 1
	v_add3_u32 v14, v14, v15, s54
	v_add_u32_e32 v15, v22, v3
	ds_write_b16_d16_hi v15, v14
	ds_read_b128 v[14:17], v4 offset:60160
	ds_read_b128 v[22:25], v4 offset:60224
	s_waitcnt lgkmcnt(1)
	v_mfma_f32_16x16x32_bf16 v[14:17], v[10:13], v[14:17], 0
	s_waitcnt lgkmcnt(0)
	v_mfma_f32_16x16x32_bf16 v[14:17], v[18:21], v[22:25], v[14:17]
	v_or_b32_e32 v22, 16, v81
	v_cmp_le_u32_e64 s[14:15], v22, v5
	v_lshl_add_u32 v23, v22, 1, s3
	s_nop 0
	v_cndmask_b32_e64 v24, 0, 1, s[14:15]
	v_cmp_ge_u32_e64 s[14:15], v22, v5
	s_nop 1
	v_cndmask_b32_e64 v25, 0, 1, s[14:15]
	v_cndmask_b32_e32 v24, v25, v24, vcc
	v_and_b32_e32 v24, 1, v24
	v_cmp_eq_u32_e64 s[14:15], 1, v24
	s_nop 1
	v_cndmask_b32_e64 v14, 0, v14, s[14:15]
	v_bfe_u32 v24, v14, 16, 1
	v_add3_u32 v14, v14, v24, s54
	v_add_u32_e32 v24, v23, v26
	v_cmp_gt_u32_e64 s[14:15], v22, v5
	ds_write_b16_d16_hi v24, v14
	s_nop 0
	v_cndmask_b32_e64 v14, 0, 1, s[14:15]
	v_cmp_le_u32_e64 s[14:15], v22, v27
	s_nop 1
	v_cndmask_b32_e64 v24, 0, 1, s[14:15]
	v_cndmask_b32_e32 v14, v14, v24, vcc
	v_and_b32_e32 v14, 1, v14
	v_cmp_eq_u32_e64 s[14:15], 1, v14
	s_nop 1
	v_cndmask_b32_e64 v14, 0, v15, s[14:15]
	v_bfe_u32 v15, v14, 16, 1
	v_add3_u32 v14, v14, v15, s54
	v_add_u32_e32 v15, v23, v28
	v_cmp_le_u32_e64 s[14:15], v22, v29
	ds_write_b16_d16_hi v15, v14
	s_nop 0
	v_cndmask_b32_e64 v14, 0, 1, s[14:15]
	v_cmp_ge_u32_e64 s[14:15], v22, v29
	s_nop 1
	v_cndmask_b32_e64 v15, 0, 1, s[14:15]
	v_cndmask_b32_e32 v14, v15, v14, vcc
	v_and_b32_e32 v14, 1, v14
	v_cmp_eq_u32_e64 s[14:15], 1, v14
	s_nop 1
	v_cndmask_b32_e64 v14, 0, v16, s[14:15]
	v_bfe_u32 v15, v14, 16, 1
	v_add3_u32 v14, v14, v15, s54
	v_add_u32_e32 v15, v23, v31
	v_cmp_le_u32_e64 s[14:15], v22, v32
	ds_write_b16_d16_hi v15, v14
	s_nop 0
	v_cndmask_b32_e64 v14, 0, 1, s[14:15]
	v_cmp_ge_u32_e64 s[14:15], v22, v32
	s_nop 1
	v_cndmask_b32_e64 v15, 0, 1, s[14:15]
	v_cndmask_b32_e32 v14, v15, v14, vcc
	v_and_b32_e32 v14, 1, v14
	v_cmp_eq_u32_e64 s[14:15], 1, v14
	s_nop 1
	v_cndmask_b32_e64 v14, 0, v17, s[14:15]
	v_bfe_u32 v15, v14, 16, 1
	v_add3_u32 v14, v14, v15, s54
	v_add_u32_e32 v15, v23, v3
	ds_write_b16_d16_hi v15, v14
	ds_read_b128 v[14:17], v4 offset:62464
	ds_read_b128 v[22:25], v4 offset:62528
	s_waitcnt lgkmcnt(1)
	v_mfma_f32_16x16x32_bf16 v[14:17], v[10:13], v[14:17], 0
	s_waitcnt lgkmcnt(0)
; #define LAS __attribute__((address_space(3)))
; __device__ __forceinline__ bf16_t f2bf(float f) { unsigned u = __float_as_uint(f); u += 0x7FFFu + ((u >> 16) & 1u); return (bf16_t)(u >> 16); }
; __device__ __forceinline__ f32x4 mfma16(bf16x8 a, bf16x8 b, f32x4 c) { return __builtin_amdgcn_mfma_f32_16x16x32_bf16(a, b, c, 0, 0, 0); }
; __device__ __forceinline__ void gla_g3_item(int wv, const Params& p, int l, int b, int n, int h, LAS unsigned char* lds) {
;     ...
;           for (int i = 0; i < 4; ++i) { const int t = mi * 16 + fq * 4 + i, sidx = ni * 16 + fr; const bool keep = dir ? (sidx >= t) : (sidx <= t);
;               *(LAS bf16_t*)(lds + GL_X + (dir * 64 + t) * 144 + sidx * 2) = f2bf(keep ? acc[i] : 0.f); } } }
;     __syncthreads();
;     LAS float* Ob = (LAS float*)lds;
;     { const int mi = wave >> 1, nb = (wave & 1) * 3;
; #pragma unroll
;       for (int nn = 0; nn < 3; ++nn) { const int ni = nb + nn; f32x4 acc = (f32x4){0.f, 0.f, 0.f, 0.f};
; #pragma unroll
;           for (int dir = 0; dir < 2; ++dir)
; #pragma unroll
;               for (int kk = 0; kk < 2; ++kk) {
;                   const bf16x8 a1 = *(const LAS bf16x8*)(lds + GL_X + (dir * 64 + mi * 16 + fr) * 144 + kk * 64 + fq * 16);
;                   const bf16x8 b1 = *(const LAS bf16x8*)(lds + GL_VT + (ni * 16 + fr) * 144 + kk * 64 + fq * 16);
;                   acc = mfma16(a1, b1, acc);
;                   const bf16x8 a2 = *(const LAS bf16x8*)(lds + GL_Q + (dir * 64 + mi * 16 + fr) * 144 + kk * 64 + fq * 16);
;                   const bf16x8 b2 = *(const LAS bf16x8*)(lds + GL_ST + (dir * 96 + ni * 16 + fr) * 144 + kk * 64 + fq * 16);
;                   acc = mfma16(a2, b2, acc); }
; #pragma unroll
;           for (int i = 0; i < 4; ++i) Ob[(mi * 16 + fq * 4 + i) * 97 + ni * 16 + fr] = acc[i]; } }
	v_mfma_f32_16x16x32_bf16 v[14:17], v[18:21], v[22:25], v[14:17]
	v_or_b32_e32 v22, 32, v81
	v_cmp_le_u32_e64 s[14:15], v22, v5
	v_lshl_add_u32 v23, v22, 1, s3
	s_nop 0
	v_cndmask_b32_e64 v24, 0, 1, s[14:15]
	v_cmp_ge_u32_e64 s[14:15], v22, v5
	s_nop 1
	v_cndmask_b32_e64 v25, 0, 1, s[14:15]
	v_cndmask_b32_e32 v24, v25, v24, vcc
	v_and_b32_e32 v24, 1, v24
	v_cmp_eq_u32_e64 s[14:15], 1, v24
	s_nop 1
	v_cndmask_b32_e64 v14, 0, v14, s[14:15]
	v_bfe_u32 v24, v14, 16, 1
	v_add3_u32 v14, v14, v24, s54
	v_add_u32_e32 v24, v23, v26
	v_cmp_gt_u32_e64 s[14:15], v22, v5
	ds_write_b16_d16_hi v24, v14
	s_nop 0
	v_cndmask_b32_e64 v14, 0, 1, s[14:15]
	v_cmp_le_u32_e64 s[14:15], v22, v27
	s_nop 1
	v_cndmask_b32_e64 v24, 0, 1, s[14:15]
	v_cndmask_b32_e32 v14, v14, v24, vcc
	v_and_b32_e32 v14, 1, v14
	v_cmp_eq_u32_e64 s[14:15], 1, v14
	s_nop 1
	v_cndmask_b32_e64 v14, 0, v15, s[14:15]
	v_bfe_u32 v15, v14, 16, 1
	v_add3_u32 v14, v14, v15, s54
	v_add_u32_e32 v15, v23, v28
	v_cmp_le_u32_e64 s[14:15], v22, v29
	ds_write_b16_d16_hi v15, v14
	s_nop 0
	v_cndmask_b32_e64 v14, 0, 1, s[14:15]
	v_cmp_ge_u32_e64 s[14:15], v22, v29
	s_nop 1
	v_cndmask_b32_e64 v15, 0, 1, s[14:15]
	v_cndmask_b32_e32 v14, v15, v14, vcc
	v_and_b32_e32 v14, 1, v14
	v_cmp_eq_u32_e64 s[14:15], 1, v14
	s_nop 1
	v_cndmask_b32_e64 v14, 0, v16, s[14:15]
	v_bfe_u32 v15, v14, 16, 1
	v_add3_u32 v14, v14, v15, s54
	v_add_u32_e32 v15, v23, v31
	v_cmp_le_u32_e64 s[14:15], v22, v32
	ds_write_b16_d16_hi v15, v14
	s_nop 0
	v_cndmask_b32_e64 v14, 0, 1, s[14:15]
	v_cmp_ge_u32_e64 s[14:15], v22, v32
	s_nop 1
	v_cndmask_b32_e64 v15, 0, 1, s[14:15]
	v_cndmask_b32_e32 v14, v15, v14, vcc
	v_and_b32_e32 v14, 1, v14
	v_cmp_eq_u32_e64 s[14:15], 1, v14
	s_nop 1
	v_cndmask_b32_e64 v14, 0, v17, s[14:15]
	v_bfe_u32 v15, v14, 16, 1
	v_add3_u32 v14, v14, v15, s54
	v_add_u32_e32 v15, v23, v3
	ds_write_b16_d16_hi v15, v14
	ds_read_b128 v[14:17], v4 offset:64768
	s_waitcnt lgkmcnt(0)
	v_mfma_f32_16x16x32_bf16 v[10:13], v[10:13], v[14:17], 0
	ds_read_b128 v[14:17], v4 offset:64832
	v_or_b32_e32 v4, 48, v81
	v_cmp_le_u32_e64 s[14:15], v4, v5
	s_waitcnt lgkmcnt(0)
	v_mfma_f32_16x16x32_bf16 v[10:13], v[18:21], v[14:17], v[10:13]
	v_cndmask_b32_e64 v15, 0, 1, s[14:15]
	v_cmp_ge_u32_e64 s[14:15], v4, v5
	v_lshl_add_u32 v14, v4, 1, s3
	v_add_u32_e32 v3, v14, v3
	v_cndmask_b32_e64 v16, 0, 1, s[14:15]
	v_cndmask_b32_e32 v15, v16, v15, vcc
	v_and_b32_e32 v15, 1, v15
	v_cmp_eq_u32_e64 s[14:15], 1, v15
	s_nop 1
	v_cndmask_b32_e64 v10, 0, v10, s[14:15]
	v_bfe_u32 v15, v10, 16, 1
	v_cmp_gt_u32_e64 s[14:15], v4, v5
	v_add3_u32 v10, v10, v15, s54
	v_add_u32_e32 v15, v14, v26
	v_cndmask_b32_e64 v5, 0, 1, s[14:15]
	v_cmp_le_u32_e64 s[14:15], v4, v27
	ds_write_b16_d16_hi v15, v10
	s_nop 0
	v_cndmask_b32_e64 v10, 0, 1, s[14:15]
	v_cndmask_b32_e32 v5, v5, v10, vcc
	v_and_b32_e32 v5, 1, v5
	v_cmp_eq_u32_e64 s[14:15], 1, v5
	s_nop 1
	v_cndmask_b32_e64 v5, 0, v11, s[14:15]
	v_bfe_u32 v10, v5, 16, 1
	v_add3_u32 v5, v5, v10, s54
	v_add_u32_e32 v10, v14, v28
	v_cmp_le_u32_e64 s[14:15], v4, v29
	ds_write_b16_d16_hi v10, v5
	s_nop 0
	v_cndmask_b32_e64 v5, 0, 1, s[14:15]
	v_cmp_ge_u32_e64 s[14:15], v4, v29
	s_nop 1
	v_cndmask_b32_e64 v10, 0, 1, s[14:15]
	v_cndmask_b32_e32 v5, v10, v5, vcc
	v_and_b32_e32 v5, 1, v5
	v_cmp_eq_u32_e64 s[14:15], 1, v5
	s_nop 1
	v_cndmask_b32_e64 v5, 0, v12, s[14:15]
	v_bfe_u32 v10, v5, 16, 1
	v_add3_u32 v5, v5, v10, s54
	v_add_u32_e32 v10, v14, v31
	v_cmp_le_u32_e64 s[14:15], v4, v32
	ds_write_b16_d16_hi v10, v5
	s_nop 0
	v_cndmask_b32_e64 v5, 0, 1, s[14:15]
	v_cmp_ge_u32_e64 s[14:15], v4, v32
	v_and_b32_e32 v32, -16, v63
	s_nop 0
	v_cndmask_b32_e64 v4, 0, 1, s[14:15]
	v_cndmask_b32_e32 v4, v4, v5, vcc
	v_and_b32_e32 v4, 1, v4
	v_cmp_eq_u32_e32 vcc, 1, v4
	s_add_u32 s14, s30, s8
	s_addc_u32 s15, s31, s9
	v_cndmask_b32_e32 v4, 0, v13, vcc
	v_cmp_ne_u32_e32 vcc, 0, v2
	v_or_b32_e32 v2, v32, v81
	v_bfe_u32 v5, v4, 16, 1
	v_mul_lo_u32 v14, v2, s55
	v_add3_u32 v4, v4, v5, s54
	v_add3_u32 v34, s3, v0, v14
	ds_write_b16_d16_hi v3, v4
	s_waitcnt lgkmcnt(0)
	s_barrier
	ds_read_b128 v[20:23], v34
	v_cndmask_b32_e64 v31, 0, 3, vcc
	v_lshl_or_b32 v29, v31, 4, v81
	v_mad_u32_u24 v15, v29, s55, v33
	v_add_u32_e32 v35, v38, v14
	v_add_u32_e32 v0, s70, v0
	v_mad_u32_u24 v36, v29, s55, v0
	ds_read_b128 v[112:115], v15
	ds_read_b128 v[116:119], v15 offset:2304
	ds_read_b128 v[120:123], v15 offset:4608
	ds_read_b128 v[24:27], v35 offset:39424
	ds_read_b128 v[124:127], v36
	ds_read_b128 v[132:135], v36 offset:2304
	ds_read_b128 v[136:139], v36 offset:4608
	v_or_b32_e32 v29, v32, v40
	v_mul_lo_u32 v32, v29, s64
	v_lshlrev_b32_e32 v37, 6, v31
	v_add3_u32 v37, v39, v37, v32
	s_waitcnt lgkmcnt(4)
	v_mfma_f32_16x16x32_bf16 v[2:5], v[20:23], v[112:115], 0
	v_mfma_f32_16x16x32_bf16 v[10:13], v[20:23], v[116:119], 0
	v_mfma_f32_16x16x32_bf16 v[16:19], v[20:23], v[120:123], 0
	ds_read_b128 v[20:23], v34 offset:64
	ds_read_b128 v[112:115], v15 offset:64
	ds_read_b128 v[116:119], v15 offset:2368
	ds_read_b128 v[120:123], v15 offset:4672
	s_waitcnt lgkmcnt(4)
	v_mfma_f32_16x16x32_bf16 v[2:5], v[24:27], v[124:127], v[2:5]
	v_mfma_f32_16x16x32_bf16 v[10:13], v[24:27], v[132:135], v[10:13]
	v_mfma_f32_16x16x32_bf16 v[16:19], v[24:27], v[136:139], v[16:19]
	ds_read_b128 v[24:27], v35 offset:39488
	ds_read_b128 v[124:127], v36 offset:64
	ds_read_b128 v[132:135], v36 offset:2368
	ds_read_b128 v[136:139], v36 offset:4672
	s_waitcnt lgkmcnt(4)
	v_mfma_f32_16x16x32_bf16 v[2:5], v[20:23], v[112:115], v[2:5]
	v_mfma_f32_16x16x32_bf16 v[10:13], v[20:23], v[116:119], v[10:13]
	v_mfma_f32_16x16x32_bf16 v[16:19], v[20:23], v[120:123], v[16:19]
	ds_read_b128 v[20:23], v34 offset:9216
	ds_read_b128 v[112:115], v15
	ds_read_b128 v[116:119], v15 offset:2304
	ds_read_b128 v[120:123], v15 offset:4608
	s_waitcnt lgkmcnt(4)
; #define LAS __attribute__((address_space(3)))
; __device__ __forceinline__ f32x4 mfma16(bf16x8 a, bf16x8 b, f32x4 c) { return __builtin_amdgcn_mfma_f32_16x16x32_bf16(a, b, c, 0, 0, 0); }
; __device__ __forceinline__ void gla_g3_item(int wv, const Params& p, int l, int b, int n, int h, LAS unsigned char* lds) {
;     ...
;     { const int mi = wave >> 1, nb = (wave & 1) * 3;
; #pragma unroll
;       for (int nn = 0; nn < 3; ++nn) { const int ni = nb + nn; f32x4 acc = (f32x4){0.f, 0.f, 0.f, 0.f};
; #pragma unroll
;           for (int dir = 0; dir < 2; ++dir)
; #pragma unroll
;               for (int kk = 0; kk < 2; ++kk) {
;                   const bf16x8 a1 = *(const LAS bf16x8*)(lds + GL_X + (dir * 64 + mi * 16 + fr) * 144 + kk * 64 + fq * 16);
;                   const bf16x8 b1 = *(const LAS bf16x8*)(lds + GL_VT + (ni * 16 + fr) * 144 + kk * 64 + fq * 16);
;                   acc = mfma16(a1, b1, acc);
;                   const bf16x8 a2 = *(const LAS bf16x8*)(lds + GL_Q + (dir * 64 + mi * 16 + fr) * 144 + kk * 64 + fq * 16);
;                   const bf16x8 b2 = *(const LAS bf16x8*)(lds + GL_ST + (dir * 96 + ni * 16 + fr) * 144 + kk * 64 + fq * 16);
;                   acc = mfma16(a2, b2, acc); }
; #pragma unroll
;           for (int i = 0; i < 4; ++i) Ob[(mi * 16 + fq * 4 + i) * 97 + ni * 16 + fr] = acc[i]; } }
	v_mfma_f32_16x16x32_bf16 v[2:5], v[24:27], v[124:127], v[2:5]
	v_mfma_f32_16x16x32_bf16 v[10:13], v[24:27], v[132:135], v[10:13]
	v_mfma_f32_16x16x32_bf16 v[16:19], v[24:27], v[136:139], v[16:19]
	ds_read_b128 v[24:27], v35 offset:48640
	ds_read_b128 v[124:127], v36 offset:13824
	ds_read_b128 v[132:135], v36 offset:16128
	ds_read_b128 v[136:139], v36 offset:18432
	s_waitcnt lgkmcnt(4)
	v_mfma_f32_16x16x32_bf16 v[2:5], v[20:23], v[112:115], v[2:5]
	v_mfma_f32_16x16x32_bf16 v[10:13], v[20:23], v[116:119], v[10:13]
	v_mfma_f32_16x16x32_bf16 v[16:19], v[20:23], v[120:123], v[16:19]
	ds_read_b128 v[20:23], v34 offset:9280
	ds_read_b128 v[112:115], v15 offset:64
	ds_read_b128 v[116:119], v15 offset:2368
	ds_read_b128 v[120:123], v15 offset:4672
	s_waitcnt lgkmcnt(4)
	v_mfma_f32_16x16x32_bf16 v[2:5], v[24:27], v[124:127], v[2:5]
	v_mfma_f32_16x16x32_bf16 v[10:13], v[24:27], v[132:135], v[10:13]
	v_mfma_f32_16x16x32_bf16 v[16:19], v[24:27], v[136:139], v[16:19]
	ds_read_b128 v[24:27], v35 offset:48704
	ds_read_b128 v[124:127], v36 offset:13888
	ds_read_b128 v[132:135], v36 offset:16192
	ds_read_b128 v[136:139], v36 offset:18496
	s_waitcnt lgkmcnt(4)
	v_mfma_f32_16x16x32_bf16 v[2:5], v[20:23], v[112:115], v[2:5]
	v_mfma_f32_16x16x32_bf16 v[10:13], v[20:23], v[116:119], v[10:13]
	v_mfma_f32_16x16x32_bf16 v[16:19], v[20:23], v[120:123], v[16:19]
	s_waitcnt lgkmcnt(0)
	v_mfma_f32_16x16x32_bf16 v[2:5], v[24:27], v[124:127], v[2:5]
	v_mfma_f32_16x16x32_bf16 v[10:13], v[24:27], v[132:135], v[10:13]
	v_mfma_f32_16x16x32_bf16 v[16:19], v[24:27], v[136:139], v[16:19]
	s_nop 7
	v_add_u32_e32 v29, 0x200, v37
	ds_write2_b32 v37, v2, v3 offset1:97
	ds_write2_b32 v29, v4, v5 offset0:66 offset1:163
	ds_write2_b32 v37, v10, v11 offset0:16 offset1:113
	ds_write2_b32 v29, v12, v13 offset0:82 offset1:179
	ds_write2_b32 v37, v16, v17 offset0:32 offset1:129
	ds_write2_b32 v29, v18, v19 offset0:98 offset1:195
	s_waitcnt vmcnt(0)
	v_lshlrev_b32_e32 v26, 16, v7
	v_and_b32_e32 v28, 0xffff0000, v7
	v_mul_lo_u32 v10, v63, s64
	v_lshlrev_b32_e32 v0, 2, v65
	s_waitcnt lgkmcnt(0)
	s_barrier
; __device__ __forceinline__ unsigned pk_bf16(float lo, float hi) { unsigned r; asm volatile("v_cvt_pk_bf16_f32 %0, %1, %2" : "=v"(r) : "v"(lo), "v"(hi)); return r; }
; __device__ __forceinline__ float bflo(unsigned w) { return __uint_as_float(w << 16); }
; __device__ __forceinline__ float bfhi(unsigned w) { return __uint_as_float(w & 0xffff0000u); }
; __device__ __forceinline__ float shx(float v, int m, int lane) { return __int_as_float(__builtin_amdgcn_ds_bpermute((lane ^ m) << 2, __float_as_int(v))); }
; __device__ __forceinline__ void gla_g3_item(int wv, const Params& p, int l, int b, int n, int h, LAS unsigned char* lds) {
;     ...
;     { const int t = tf; float o[12]; float ss = 0.f;
; #pragma unroll
;       for (int e = 0; e < 12; ++e) { o[e] = Ob[t * 97 + part * 12 + e]; ss += o[e] * o[e]; }
;       ss += shx(ss, 1, lane); ss += shx(ss, 2, lane); ss += shx(ss, 4, lane);
;       const float rs = rsqrtf(ss * (1.0f / 96.0f) + 1e-6f);
;       const float* gn = p.gla_o_norm + l * 96 + part * 12;
;       bf16_t* yp = (bf16_t*)(p.ws + OFF_HY) + (size_t)(row0 + t) * 1024 + 640 + h * 96 + part * 12;
; #pragma unroll
;       for (int q4 = 0; q4 < 3; ++q4) { const u32x2 gw = ggw[q4]; float g[4] = {bflo(gw.x), bfhi(gw.x), bflo(gw.y), bfhi(gw.y)}; float r[4];
; #pragma unroll
;           for (int e = 0; e < 4; ++e) r[e] = o[q4 * 4 + e] * rs * gn[q4 * 4 + e] * (g[e] * __builtin_amdgcn_rcpf(1.f + __expf(-g[e])));
;           u32x2 w; w.x = pk_bf16(r[0], r[1]); w.y = pk_bf16(r[2], r[3]); *(u32x2*)(yp + q4 * 4) = w; } }
	global_load_dwordx4 v[2:5], v0, s[14:15]
	global_load_dwordx4 v[144:147], v0, s[14:15] offset:16
	global_load_dwordx4 v[148:151], v0, s[14:15] offset:32
	v_add3_u32 v22, 0, v10, v0
	ds_read2_b32 v[10:11], v22 offset1:1
	ds_read2_b32 v[12:13], v22 offset0:2 offset1:3
	ds_read2_b32 v[14:15], v22 offset0:4 offset1:5
	ds_read2_b32 v[16:17], v22 offset0:6 offset1:7
	s_waitcnt lgkmcnt(3)
	v_mul_f32_e32 v20, v11, v11
	v_fmac_f32_e32 v20, v10, v10
	s_waitcnt lgkmcnt(2)
	v_fmac_f32_e32 v20, v12, v12
	v_fmac_f32_e32 v20, v13, v13
	s_waitcnt lgkmcnt(1)
	v_pk_mul_f32 v[18:19], v[14:15], v[14:15]
	s_waitcnt vmcnt(0)
	v_mov_b32_e32 v31, v2
	v_add_f32_e32 v18, v20, v18
	v_add_f32_e32 v23, v18, v19
	ds_read2_b32 v[18:19], v22 offset0:8 offset1:9
	s_waitcnt lgkmcnt(1)
	v_pk_mul_f32 v[20:21], v[16:17], v[16:17]
	s_nop 0
	v_add_f32_e32 v20, v23, v20
	ds_read2_b32 v[22:23], v22 offset0:10 offset1:11
	v_add_f32_e32 v24, v20, v21
	s_waitcnt lgkmcnt(1)
	v_pk_mul_f32 v[20:21], v[18:19], v[18:19]
	s_nop 0
	v_add_f32_e32 v20, v24, v20
	v_add_f32_e32 v24, v20, v21
	s_waitcnt lgkmcnt(0)
	v_pk_mul_f32 v[20:21], v[22:23], v[22:23]
	s_nop 0
	v_add_f32_e32 v20, v24, v20
	v_add_f32_e32 v20, v20, v21
	v_lshlrev_b32_e32 v21, 2, v30
	v_xor_b32_e32 v24, 4, v21
	s_nop 1
	v_mov_b32_dpp v24, v20 quad_perm:[1,0,3,2] row_mask:0xf bank_mask:0xf
	s_waitcnt lgkmcnt(0)
	v_add_f32_e32 v20, v20, v24
	v_xor_b32_e32 v24, 8, v21
	s_nop 1
	v_mov_b32_dpp v24, v20 quad_perm:[2,3,0,1] row_mask:0xf bank_mask:0xf
	v_xor_b32_e32 v21, 16, v21
	s_waitcnt lgkmcnt(0)
	v_add_f32_e32 v20, v20, v24
	s_nop 1
	v_mov_b32_dpp v21, v20 row_half_mirror row_mask:0xf bank_mask:0xf
	v_lshlrev_b32_e32 v24, 16, v6
	v_and_b32_e32 v6, 0xffff0000, v6
	v_mul_f32_e32 v7, 0xbfb8aa3b, v24
	v_exp_f32_e32 v7, v7
	s_waitcnt lgkmcnt(0)
	v_add_f32_e32 v20, v20, v21
	v_fmamk_f32 v20, v20, 0x3c2aaaab, v197
	v_mul_f32_e32 v21, 0x4b800000, v20
	v_cmp_gt_f32_e32 vcc, s68, v20
	v_add_f32_e32 v7, 1.0, v7
	v_rcp_f32_e32 v30, v7
	v_cndmask_b32_e32 v20, v20, v21, vcc
	v_rsq_f32_e32 v20, v20
	s_nop 0
	v_mul_f32_e32 v21, 0x45800000, v20
	v_cndmask_b32_e32 v32, v20, v21, vcc
	v_mul_f32_e32 v25, v10, v32
	v_mul_f32_e32 v10, 0xbfb8aa3b, v6
	v_exp_f32_e32 v10, v10
	v_mul_f32_e32 v7, v11, v32
	v_lshlrev_b64 v[20:21], 11, v[58:59]
	v_lshl_add_u64 v[20:21], s[6:7], 0, v[20:21]
	v_add_f32_e32 v2, 1.0, v10
	v_rcp_f32_e32 v2, v2
	v_lshl_add_u64 v[20:21], v[20:21], 0, s[56:57]
	v_mul_f32_e32 v27, v12, v32
	v_lshl_add_u64 v[20:21], v[20:21], 0, v[60:61]
	v_pk_mul_f32 v[2:3], v[2:3], v[6:7]
	v_mul_f32_e32 v29, v13, v32
	v_mul_f32_e32 v6, v2, v3
	v_mul_f32_e32 v2, 0xbfb8aa3b, v26
	v_exp_f32_e32 v2, v2
	v_mul_f32_e32 v3, 0xbfb8aa3b, v28
	v_exp_f32_e32 v7, v3
	v_mov_b32_e32 v3, v4
	v_add_f32_e32 v2, 1.0, v2
	v_rcp_f32_e32 v2, v2
	v_add_f32_e32 v4, 1.0, v7
	v_rcp_f32_e32 v4, v4
	v_pk_mul_f32 v[24:25], v[30:31], v[24:25]
	v_pk_mul_f32 v[2:3], v[2:3], v[26:27]
	v_mul_f32_e32 v10, v24, v25
	v_mul_f32_e32 v7, v2, v3
	v_pk_mul_f32 v[2:3], v[4:5], v[28:29]
	v_add_co_u32_e32 v4, vcc, s68, v20
	v_mul_f32_e32 v3, v2, v3
	s_nop 0
	v_addc_co_u32_e32 v5, vcc, 0, v21, vcc
	v_cvt_pk_bf16_f32 v2, v10, v6
	v_cvt_pk_bf16_f32 v3, v7, v3
	global_store_dwordx2 v[4:5], v[2:3], off offset:1280
	v_lshlrev_b32_e32 v10, 16, v8
	v_mul_f32_e32 v11, 0xbfb8aa3b, v10
	v_exp_f32_e32 v13, v11
	v_lshl_add_u64 v[6:7], v[20:21], 0, s[4:5]
	v_and_b32_e32 v8, 0xffff0000, v8
	v_lshlrev_b32_e32 v12, 16, v9
	v_and_b32_e32 v20, 0xffff0000, v9
	v_add_f32_e32 v9, 1.0, v13
	v_rcp_f32_e32 v24, v9
	v_mul_f32_e32 v9, 0xbfb8aa3b, v8
	v_exp_f32_e32 v9, v9
	v_mul_f32_e32 v11, v14, v32
	v_mov_b32_e32 v2, v144
	v_mov_b32_e32 v3, v145
	v_mov_b32_e32 v4, v146
	v_mov_b32_e32 v5, v147
	v_mov_b32_e32 v25, v2
	v_add_f32_e32 v2, 1.0, v9
	v_rcp_f32_e32 v2, v2
	v_pk_mul_f32 v[10:11], v[24:25], v[10:11]
	v_mul_f32_e32 v9, 0xbfb8aa3b, v12
	v_mul_f32_e32 v10, v10, v11
	v_exp_f32_e32 v11, v9
	v_mul_f32_e32 v9, v15, v32
	v_pk_mul_f32 v[2:3], v[2:3], v[8:9]
	v_mov_b32_e32 v13, v4
	v_mul_f32_e32 v14, v2, v3
	v_mul_f32_e32 v3, 0xbfb8aa3b, v20
	v_exp_f32_e32 v8, v3
	v_add_f32_e32 v2, 1.0, v11
	v_rcp_f32_e32 v2, v2
	v_mul_f32_e32 v3, v16, v32
	v_add_f32_e32 v4, 1.0, v8
	v_rcp_f32_e32 v8, v4
	v_pk_mul_f32 v[2:3], v[2:3], v[12:13]
	v_mul_f32_e32 v9, v17, v32
	v_mov_b32_e32 v21, v5
	v_mul_f32_e32 v4, v2, v3
	v_pk_mul_f32 v[2:3], v[8:9], v[20:21]
	v_lshlrev_b32_e32 v8, 16, v46
	v_mul_f32_e32 v3, v2, v3
	v_cvt_pk_bf16_f32 v2, v10, v14
	v_cvt_pk_bf16_f32 v3, v4, v3
	global_store_dwordx2 v[6:7], v[2:3], off offset:8
	v_mul_f32_e32 v0, 0xbfb8aa3b, v8
	v_exp_f32_e32 v0, v0
	v_and_b32_e32 v10, 0xffff0000, v46
	v_mul_f32_e32 v17, v18, v32
	v_lshlrev_b32_e32 v12, 16, v47
	v_add_f32_e32 v0, 1.0, v0
	v_rcp_f32_e32 v16, v0
	v_mul_f32_e32 v0, 0xbfb8aa3b, v10
	v_exp_f32_e32 v0, v0
	v_and_b32_e32 v14, 0xffff0000, v47
	v_add_f32_e32 v0, 1.0, v0
	v_mov_b32_e32 v2, v148
	v_mov_b32_e32 v3, v149
	v_mov_b32_e32 v4, v150
	v_mov_b32_e32 v5, v151
	v_mov_b32_e32 v9, v2
	v_pk_mul_f32 v[8:9], v[16:17], v[8:9]
	v_mov_b32_e32 v11, v3
	v_mul_f32_e32 v16, v8, v9
	v_rcp_f32_e32 v8, v0
	v_mul_f32_e32 v0, 0xbfb8aa3b, v12
	v_exp_f32_e32 v0, v0
	v_mul_f32_e32 v9, v19, v32
	v_pk_mul_f32 v[2:3], v[8:9], v[10:11]
	v_mov_b32_e32 v13, v4
	v_add_f32_e32 v0, 1.0, v0
	v_mul_f32_e32 v10, v2, v3
	v_rcp_f32_e32 v2, v0
	v_mul_f32_e32 v0, 0xbfb8aa3b, v14
	v_exp_f32_e32 v0, v0
	v_mul_f32_e32 v3, v22, v32
	v_pk_mul_f32 v[2:3], v[2:3], v[12:13]
	v_mul_f32_e32 v9, v23, v32
	v_add_f32_e32 v0, 1.0, v0
	v_rcp_f32_e32 v8, v0
	v_mov_b32_e32 v15, v5
	v_mul_f32_e32 v0, v2, v3
	v_pk_mul_f32 v[2:3], v[8:9], v[14:15]
	s_nop 0
	v_mul_f32_e32 v3, v2, v3
	v_cvt_pk_bf16_f32 v2, v16, v10
	v_cvt_pk_bf16_f32 v3, v0, v3
	global_store_dwordx2 v[6:7], v[2:3], off offset:16
